# baseline (speedup 1.0000x reference)
.LBB0_343:
	s_mov_b32 s4, s2
	s_and_b32 s18, s4, 7
	s_cmp_lg_u32 s24, 0
	s_barrier
	s_cbranch_scc0 .LBB0_352
	v_mov_b32_e32 v1, v170
	s_nop 0
	v_cmp_eq_u32_e32 vcc, 0, v1
	s_and_saveexec_b64 s[16:17], vcc
	s_cbranch_execz .LBB0_346
	s_mov_b32 s4, s34
	s_ashr_i32 s19, s4, 3
	s_lshl_b32 s4, s18, 2
	s_add_u32 s4, s22, s4
	s_addc_u32 s5, s23, 0
	v_mov_b64_e32 v[2:3], s[4:5]
	v_mov_b32_e32 v1, v253
	s_mov_b64 s[4:5], src_shared_base
	v_mov_b32_e32 v147, s5
	s_waitcnt vmcnt(0) lgkmcnt(0)
	v_add_u32_e32 v1, s19, v1
	flat_store_dword v[146:147], v1 sc0 sc1
	s_waitcnt vmcnt(0)

.LBB0_348:
	s_cmpk_gt_i32 s16, 0xff
	s_mov_b64 s[4:5], -1
	s_cbranch_scc1 .LBB0_342
	s_ashr_i32 s4, s16, 31
	s_lshr_b32 s4, s4, 26
	s_add_i32 s4, s16, s4
	s_andn2_b32 s4, s4, 63
	s_sub_i32 s16, s16, s4
	s_ashr_i32 s5, s16, 3
	s_lshl_b32 s16, s16, 3
	s_and_b32 s16, s16, 56
	s_or_b32 s4, s4, s16
	s_mul_i32 s16, s5, 0x56000
	v_mov_b32_e32 v1, v170
	s_barrier
	s_or_b32 s4, s4, s18
	s_ashr_i32 s17, s16, 31
	s_lshl_b32 s4, s4, 8
	v_lshlrev_b32_e32 v145, 4, v1
	s_lshl_b64 s[16:17], s[16:17], 1
	v_add_u32_e32 v29, 0x1000, v145
	v_add_u32_e32 v30, 0x2000, v145
	v_add_u32_e32 v32, 0x3000, v145
	s_add_u32 s18, s20, s16
	v_and_b32_e32 v26, 32, v1
	v_bfe_u32 v27, v1, 2, 4
	v_ashrrev_i32_e32 v13, 2, v1
	v_ashrrev_i32_e32 v15, 6, v29
	v_ashrrev_i32_e32 v10, 6, v30
	v_ashrrev_i32_e32 v16, 6, v32
	s_addc_u32 s19, s21, s17
	v_lshrrev_b32_e32 v14, 2, v1
	v_bitop3_b32 v2, v145, v26, 48 bitop3:0x6c
	v_or_b32_e32 v12, s4, v27
	v_mov_b32_e32 v3, v0
	v_and_b32_e32 v6, -16, v13
	v_and_b32_e32 v8, -16, v15
	v_and_b32_e32 v31, -16, v10
	v_and_b32_e32 v33, -16, v16
	v_lshl_add_u64 v[4:5], s[38:39], 0, v[2:3]
	v_add_u32_e32 v6, v12, v6
	v_add_u32_e32 v8, v8, v12
	v_add_u32_e32 v10, v31, v12
	v_add_u32_e32 v12, v33, v12
	v_lshl_add_u64 v[2:3], s[18:19], 0, v[2:3]
	v_bfi_b32 v34, 15, v14, v13
	v_bfi_b32 v35, -16, v15, v14
	v_mad_i64_i32 v[6:7], s[26:27], v6, s3, v[4:5]
	v_mad_i64_i32 v[8:9], s[26:27], v8, s3, v[4:5]
	v_mad_i64_i32 v[10:11], s[26:27], v10, s3, v[4:5]
	v_mad_i64_i32 v[4:5], s[26:27], v12, s3, v[4:5]
	v_mad_i64_i32 v[12:13], s[18:19], v34, s3, v[2:3]
	v_mad_i64_i32 v[2:3], s[18:19], v35, s3, v[2:3]
	v_readfirstlane_b32 s18, v145
	s_waitcnt vmcnt(0)
	s_mov_b32 m0, s18
	v_readfirstlane_b32 s18, v29
	s_mov_b32 m0, s18
	v_readfirstlane_b32 s18, v30
	v_add_u32_e32 v36, 0x4000, v145
	s_mov_b32 m0, s18
	v_readfirstlane_b32 s18, v32
	v_add_u32_e32 v37, 0x5000, v145
	s_mov_b32 m0, s18
	v_readfirstlane_b32 s18, v36
	v_add_u32_e32 v38, 0x6000, v145
	s_mov_b32 m0, s18
	v_readfirstlane_b32 s18, v37
	v_and_b32_e32 v142, 15, v1
	v_bfe_u32 v143, v1, 4, 2
	v_lshlrev_b32_e32 v17, 6, v1
	v_lshlrev_b32_e32 v14, 2, v1
	v_add_u32_e32 v39, 0x7000, v145
	s_mov_b32 m0, s18
	v_readfirstlane_b32 s18, v38
	v_lshlrev_b32_e32 v16, 4, v143
	v_and_b32_e32 v18, 0x3c0, v17
	v_lshlrev_b32_e32 v19, 6, v142
	v_and_b32_e32 v20, 32, v14
	v_lshl_add_u64 v[14:15], v[6:7], 0, 64
	v_add_u32_e32 v40, 0x8000, v145
	s_mov_b32 m0, s18
	v_readfirstlane_b32 s18, v39
	v_add_u32_e32 v41, 0x9000, v145
	v_and_b32_e32 v147, 0xfffff000, v17
	v_bitop3_b32 v149, v16, v20, v18 bitop3:0x36
	v_bitop3_b32 v144, v16, v20, v19 bitop3:0x36
	v_lshl_add_u64 v[16:17], v[8:9], 0, 64
	s_mov_b32 m0, s18
	v_readfirstlane_b32 s18, v40
	v_add_u32_e32 v42, 0xa000, v145
	v_lshl_add_u64 v[18:19], v[10:11], 0, 64
	s_mov_b32 m0, s18
	v_readfirstlane_b32 s18, v41
	v_add_u32_e32 v43, 0xb000, v145
	v_lshl_add_u64 v[20:21], v[4:5], 0, 64
	s_mov_b32 m0, s18
	v_readfirstlane_b32 s18, v42
	v_lshl_add_u64 v[22:23], v[12:13], 0, 64
	s_mov_b32 m0, s18
	v_readfirstlane_b32 s18, v43
	v_lshl_add_u64 v[24:25], v[2:3], 0, 64
	s_mov_b32 m0, s18
	v_mov_b64_e32 v[2:3], s[16:17]
	v_and_b32_e32 v28, 48, v145
	v_mad_i64_i32 v[4:5], s[16:17], v35, s3, v[2:3]
	v_mad_i64_i32 v[2:3], s[16:17], v34, s3, v[2:3]
	v_bitop3_b32 v2, v2, v28, v26 bitop3:0xf6
	v_lshl_add_u64 v[132:133], s[12:13], 0, v[2:3]
	v_add_u32_e32 v2, s4, v33
	v_or_b32_e32 v2, v2, v27
	v_mad_i64_i32 v[2:3], s[16:17], v2, s3, 0
	v_bitop3_b32 v2, v2, v28, v26 bitop3:0xf6
	v_lshl_add_u64 v[134:135], s[14:15], 0, v[2:3]
	v_add_u32_e32 v2, s4, v31
	v_or_b32_e32 v2, v2, v27
	v_mad_i64_i32 v[2:3], s[16:17], v2, s3, 0
	v_bitop3_b32 v2, v2, v28, v26 bitop3:0xf6
	v_lshl_add_u64 v[136:137], s[14:15], 0, v[2:3]
	v_add_u32_e32 v2, s4, v35
	v_mad_i64_i32 v[2:3], s[16:17], v2, s3, 0
	v_bitop3_b32 v2, v2, v28, v26 bitop3:0xf6
	v_lshl_add_u64 v[138:139], s[14:15], 0, v[2:3]
	v_add_u32_e32 v2, s4, v34
	v_mad_i64_i32 v[2:3], s[16:17], v2, s3, 0
	v_bitop3_b32 v2, v2, v28, v26 bitop3:0xf6
	v_bitop3_b32 v4, v4, v28, v26 bitop3:0xf6
	v_lshl_add_u64 v[140:141], s[14:15], 0, v[2:3]
	v_mov_b32_e32 v2, 0
	v_lshl_add_u64 v[130:131], s[12:13], 0, v[4:5]
	s_mov_b32 s18, 0
	s_mov_b64 s[16:17], 0
	v_mov_b32_e32 v3, v2
	v_mov_b32_e32 v4, v2
	v_mov_b32_e32 v5, v2
	v_mov_b32_e32 v6, v2
	v_mov_b32_e32 v7, v2
	v_mov_b32_e32 v8, v2
	v_mov_b32_e32 v9, v2
	v_mov_b32_e32 v10, v2
	v_mov_b32_e32 v11, v2
	v_mov_b32_e32 v12, v2
	v_mov_b32_e32 v13, v2
	v_mov_b32_e32 v14, v2
	v_mov_b32_e32 v15, v2
	v_mov_b32_e32 v16, v2
	v_mov_b32_e32 v17, v2
	v_mov_b32_e32 v18, v2
	v_mov_b32_e32 v19, v2
	v_mov_b32_e32 v20, v2
	v_mov_b32_e32 v21, v2
	v_mov_b32_e32 v26, v2
	v_mov_b32_e32 v27, v2
	v_mov_b32_e32 v28, v2
	v_mov_b32_e32 v29, v2
	v_mov_b32_e32 v38, v2
	v_mov_b32_e32 v39, v2
	v_mov_b32_e32 v40, v2
	v_mov_b32_e32 v41, v2
	v_mov_b32_e32 v54, v2
	v_mov_b32_e32 v55, v2
	v_mov_b32_e32 v56, v2
	v_mov_b32_e32 v57, v2
	v_mov_b32_e32 v22, v2
	v_mov_b32_e32 v23, v2
	v_mov_b32_e32 v24, v2
	v_mov_b32_e32 v25, v2
	v_mov_b32_e32 v30, v2
	v_mov_b32_e32 v31, v2
	v_mov_b32_e32 v32, v2
	v_mov_b32_e32 v33, v2
	v_mov_b32_e32 v34, v2
	v_mov_b32_e32 v35, v2
	v_mov_b32_e32 v36, v2
	v_mov_b32_e32 v37, v2
	v_mov_b32_e32 v42, v2
	v_mov_b32_e32 v43, v2
	v_mov_b32_e32 v44, v2
	v_mov_b32_e32 v45, v2
	v_mov_b32_e32 v46, v2
	v_mov_b32_e32 v47, v2
	v_mov_b32_e32 v48, v2
	v_mov_b32_e32 v49, v2
	v_mov_b32_e32 v58, v2
	v_mov_b32_e32 v59, v2
	v_mov_b32_e32 v60, v2
	v_mov_b32_e32 v61, v2
	v_mov_b32_e32 v70, v2
	v_mov_b32_e32 v71, v2
	v_mov_b32_e32 v72, v2
	v_mov_b32_e32 v73, v2
	v_mov_b32_e32 v86, v2
	v_mov_b32_e32 v87, v2
	v_mov_b32_e32 v88, v2
	v_mov_b32_e32 v89, v2
	v_mov_b32_e32 v50, v2
	v_mov_b32_e32 v51, v2
	v_mov_b32_e32 v52, v2
	v_mov_b32_e32 v53, v2
	v_mov_b32_e32 v62, v2
	v_mov_b32_e32 v63, v2
	v_mov_b32_e32 v64, v2
	v_mov_b32_e32 v65, v2
	v_mov_b32_e32 v66, v2
	v_mov_b32_e32 v67, v2
	v_mov_b32_e32 v68, v2
	v_mov_b32_e32 v69, v2
	v_mov_b32_e32 v74, v2
	v_mov_b32_e32 v75, v2
	v_mov_b32_e32 v76, v2
	v_mov_b32_e32 v77, v2
	v_mov_b32_e32 v78, v2
	v_mov_b32_e32 v79, v2
	v_mov_b32_e32 v80, v2
	v_mov_b32_e32 v81, v2
	v_mov_b32_e32 v90, v2
	v_mov_b32_e32 v91, v2
	v_mov_b32_e32 v92, v2
	v_mov_b32_e32 v93, v2
	v_mov_b32_e32 v102, v2
	v_mov_b32_e32 v103, v2
	v_mov_b32_e32 v104, v2
	v_mov_b32_e32 v105, v2
	v_mov_b32_e32 v114, v2
	v_mov_b32_e32 v115, v2
	v_mov_b32_e32 v116, v2
	v_mov_b32_e32 v117, v2
	v_mov_b32_e32 v82, v2
	v_mov_b32_e32 v83, v2
	v_mov_b32_e32 v84, v2
	v_mov_b32_e32 v85, v2
	v_mov_b32_e32 v94, v2
	v_mov_b32_e32 v95, v2
	v_mov_b32_e32 v96, v2
	v_mov_b32_e32 v97, v2
	v_mov_b32_e32 v98, v2
	v_mov_b32_e32 v99, v2
	v_mov_b32_e32 v100, v2
	v_mov_b32_e32 v101, v2
	v_mov_b32_e32 v106, v2
	v_mov_b32_e32 v107, v2
	v_mov_b32_e32 v108, v2
	v_mov_b32_e32 v109, v2
	v_mov_b32_e32 v110, v2
	v_mov_b32_e32 v111, v2
	v_mov_b32_e32 v112, v2
	v_mov_b32_e32 v113, v2
	v_mov_b32_e32 v118, v2
	v_mov_b32_e32 v119, v2
	v_mov_b32_e32 v120, v2
	v_mov_b32_e32 v121, v2
	v_mov_b32_e32 v122, v2
	v_mov_b32_e32 v123, v2
	v_mov_b32_e32 v124, v2
	v_mov_b32_e32 v125, v2
	v_mov_b32_e32 v126, v2
	v_mov_b32_e32 v127, v2
	v_mov_b32_e32 v128, v2
	v_mov_b32_e32 v129, v2
	s_and_b32 s32, s2, 7
	s_lshl_b32 s32, s32, 2
	s_add_u32 s18, s22, s32
	s_addc_u32 s19, s23, 0
	v_mov_b32_e32 v154, s18
	v_mov_b32_e32 v155, s19
	v_cmp_eq_u32_e32 vcc, 0, v170
	s_and_saveexec_b64 s[18:19], vcc
	global_atomic_add v253, v[154:155], v171, off sc0
	s_mov_b64 exec, s[18:19]
	v_and_b32_e32 v154, 63, v170
	v_lshrrev_b32_e32 v155, 3, v154
	v_and_b32_e32 v156, 7, v154
	v_xor_b32_e32 v156, v156, v155
	v_lshrrev_b32_e32 v157, 6, v170
	v_lshl_add_u32 v158, v157, 6, v155
	v_add_u32_e32 v158, s4, v158
	v_mul_u32_u24_e32 v224, 0x1580, v158
	v_lshl_add_u32 v224, v156, 4, v224
	v_lshl_add_u32 v158, v157, 5, v155
	v_mul_u32_u24_e32 v225, 0x1580, v158
	v_lshl_add_u32 v225, v156, 4, v225
	v_and_b32_e32 v155, 15, v154
	v_lshrrev_b32_e32 v156, 4, v154
	v_and_b32_e32 v158, 7, v155
	v_xor_b32_e32 v156, v156, v158
	v_lshlrev_b32_e32 v156, 4, v156
	v_lshl_add_u32 v229, v155, 7, v156
	v_lshl_add_u32 v227, v157, 13, v229
	v_xor_b32_e32 v228, 64, v227
	v_add_u32_e32 v229, 0xc000, v229
	v_xor_b32_e32 v230, 64, v229
	s_mov_b32 s18, s38
	s_mov_b32 s19, s39
	s_mul_i32 s32, s5, 0xac000
	s_add_u32 s16, s20, s32
	s_addc_u32 s17, s21, 0
	s_mov_b32 s25, 0
	v_readfirstlane_b32 s32, v145
	s_lshl_b32 m0, s32, 3
	v_mov_b32_e32 v226, v224
	global_load_lds_dwordx4 v226, s[18:19]
	s_add_u32 m0, m0, 0x400
	v_add_u32_e32 v226, 0xac00, v224
	global_load_lds_dwordx4 v226, s[18:19]
	s_add_u32 m0, m0, 0x400
	v_add_u32_e32 v226, 0x15800, v224
	global_load_lds_dwordx4 v226, s[18:19]
	s_add_u32 m0, m0, 0x400
	v_add_u32_e32 v226, 0x20400, v224
	global_load_lds_dwordx4 v226, s[18:19]
	s_add_u32 m0, m0, 0x400
	v_add_u32_e32 v226, 0x2b000, v224
	global_load_lds_dwordx4 v226, s[18:19]
	s_add_u32 m0, m0, 0x400
	v_add_u32_e32 v226, 0x35c00, v224
	global_load_lds_dwordx4 v226, s[18:19]
	s_add_u32 m0, m0, 0x400
	v_add_u32_e32 v226, 0x40800, v224
	global_load_lds_dwordx4 v226, s[18:19]
	s_add_u32 m0, m0, 0x400
	v_add_u32_e32 v226, 0x4b400, v224
	global_load_lds_dwordx4 v226, s[18:19]
	v_readfirstlane_b32 s32, v145
	s_lshl_b32 s32, s32, 2
	s_add_u32 m0, s32, 0xc000
	v_mov_b32_e32 v226, v225
	global_load_lds_dwordx4 v226, s[16:17]
	s_add_u32 m0, m0, 0x400
	v_add_u32_e32 v226, 0xac00, v225
	global_load_lds_dwordx4 v226, s[16:17]
	s_add_u32 m0, m0, 0x400
	v_add_u32_e32 v226, 0x15800, v225
	global_load_lds_dwordx4 v226, s[16:17]
	s_add_u32 m0, m0, 0x400
	v_add_u32_e32 v226, 0x20400, v225
	global_load_lds_dwordx4 v226, s[16:17]

.LBB0_358:
	s_mov_b32 s4, s2
	s_and_b32 s21, s4, 7
	s_cmp_lg_u32 s40, 0
	s_barrier
	s_cbranch_scc0 .LBB0_369
	v_mov_b32_e32 v1, v170
	s_nop 0
	v_cmp_eq_u32_e32 vcc, 0, v1
	s_and_saveexec_b64 s[22:23], vcc
	s_cbranch_execz .LBB0_361
	s_mov_b32 s4, s34
	s_ashr_i32 s24, s4, 3
	s_lshl_b32 s4, s21, 2
	s_add_u32 s4, s28, s4
	s_addc_u32 s5, s29, 0
	v_mov_b64_e32 v[2:3], s[4:5]
	v_mov_b32_e32 v1, v253
	s_mov_b64 s[4:5], src_shared_base
	v_mov_b32_e32 v147, s5
	s_waitcnt vmcnt(0) lgkmcnt(0)
	v_add_u32_e32 v1, s24, v1
	flat_store_dword v[146:147], v1 sc0 sc1
	s_waitcnt vmcnt(0)

.LBB0_373:
	v_mov_b32_e32 v1, v170
	s_barrier
	s_lshl_b32 s46, s41, 1
	v_ashrrev_i32_e32 v2, 7, v1
	v_add_u32_e32 v3, s46, v2
	v_cmp_lt_i32_e32 vcc, s91, v3
	s_and_saveexec_b64 s[4:5], vcc
	s_xor_b64 s[22:23], exec, s[4:5]
	v_add_u32_e32 v3, 0xfffffef0, v3
	v_mul_hi_u32 v2, v3, s96
	v_lshrrev_b32_e32 v4, 3, v2
	v_add_u32_e32 v2, 16, v4
	v_lshl_add_u32 v4, v4, 5, v4
	v_sub_u32_e32 v6, v3, v4
	s_andn2_saveexec_b64 s[22:23], s[22:23]
	v_mul_hi_i32 v2, v3, s97
	v_lshrrev_b32_e32 v4, 31, v2
	v_ashrrev_i32_e32 v2, 3, v2
	v_add_u32_e32 v2, v2, v4
	v_lshl_add_u32 v4, v2, 4, v2
	v_sub_u32_e32 v6, v3, v4
	s_or_b64 exec, exec, s[22:23]
	v_cmp_lt_i32_e32 vcc, 15, v2
	s_and_saveexec_b64 s[4:5], vcc
	s_xor_b64 s[4:5], exec, s[4:5]
	v_add_u32_e32 v2, -16, v2
	v_mov_b32_e32 v3, v0
	v_lshlrev_b64 v[2:3], 12, v[2:3]
	v_lshl_add_u64 v[4:5], v[2:3], 0, s[42:43]
	s_andn2_saveexec_b64 s[22:23], s[4:5]
	v_ashrrev_i32_e32 v3, 31, v2
	v_lshlrev_b64 v[4:5], 11, v[2:3]
	s_or_b64 exec, exec, s[22:23]
	v_mad_u64_u32 v[2:3], s[4:5], v6, s54, -1
	v_ashrrev_i32_e32 v3, 31, v2
	v_and_b32_e32 v6, 0x7f, v1
	v_mov_b32_e32 v7, v0
	v_lshl_add_u64 v[2:3], v[2:3], 0, v[6:7]
	v_lshl_add_u64 v[2:3], v[2:3], 0, v[4:5]
	v_cmp_lt_i64_e32 vcc, 0, v[2:3]
	s_nop 1
	v_cndmask_b32_e32 v3, 0, v3, vcc
	v_cndmask_b32_e32 v2, 0, v2, vcc
	v_cmp_gt_i64_e32 vcc, s[44:45], v[2:3]
	v_mov_b32_e32 v3, v0
	s_nop 0
	v_cndmask_b32_e32 v2, v174, v2, vcc
	v_lshlrev_b32_e32 v2, 6, v2
	v_lshl_add_u64 v[14:15], s[8:9], 0, v[2:3]
	flat_load_dwordx4 v[2:5], v[14:15]
	flat_load_dwordx4 v[6:9], v[14:15] offset:16
	flat_load_dwordx4 v[10:13], v[14:15] offset:32
	s_waitcnt vmcnt(0) lgkmcnt(0)
	v_mov_b32_e32 v16, v3
	v_mov_b32_e32 v17, v4
	v_mov_b32_e32 v3, v5
	v_mov_b32_e32 v18, v7
	v_mov_b32_e32 v19, v8
	v_pk_add_f32 v[2:3], v[16:17], v[2:3]
	v_mov_b32_e32 v7, v9
	v_pk_add_f32 v[16:17], v[2:3], v[2:3] op_sel:[0,1] op_sel_hi:[1,0]
	v_pk_add_f32 v[2:3], v[18:19], v[6:7]
	s_nop 0
	v_pk_add_f32 v[6:7], v[2:3], v[2:3] op_sel:[0,1] op_sel_hi:[1,0]
	v_mov_b32_e32 v2, v11
	v_pk_add_f32 v[8:9], v[10:11], v[2:3]
	v_mov_b32_e32 v2, v13
	v_pk_add_f32 v[10:11], v[12:13], v[2:3]
	flat_load_dwordx4 v[2:5], v[14:15] offset:48
	s_waitcnt vmcnt(0) lgkmcnt(0)
	v_mov_b32_e32 v17, v2
	v_mov_b32_e32 v7, v3
	v_mov_b32_e32 v9, v4
	v_mov_b32_e32 v11, v5
	v_pk_add_f32 v[2:3], v[16:17], v[6:7]
	v_pk_add_f32 v[4:5], v[8:9], v[10:11]
	v_ashrrev_i32_e32 v6, 6, v1
	v_pk_add_f32 v[2:3], v[2:3], v[4:5]
	s_nop 0
	v_add_f32_e32 v2, v2, v3
	v_fmamk_f32 v2, v2, 0x3a800000, v172
	v_cmp_gt_f32_e32 vcc, s58, v2
	v_mul_f32_e32 v3, 0x4b800000, v2
	s_nop 0
	v_cndmask_b32_e32 v2, v2, v3, vcc
	v_rsq_f32_e32 v2, v2
	s_nop 0
	v_mul_f32_e32 v3, 0x45800000, v2
	v_cndmask_b32_e32 v2, v2, v3, vcc
	v_lshl_add_u32 v3, v1, 2, v175
	ds_write_b32 v3, v2
	v_and_b32_e32 v3, 63, v1
	v_cmp_lt_i32_e32 vcc, 2, v6
	s_and_saveexec_b64 s[4:5], vcc
	s_xor_b64 s[4:5], exec, s[4:5]
	v_lshl_or_b32 v2, s20, 6, v3
	s_or_saveexec_b64 s[22:23], s[4:5]
	v_mov_b64_e32 v[4:5], s[14:15]
	s_xor_b64 exec, exec, s[22:23]
	s_movk_i32 s4, 0xac0
	v_mul_lo_u32 v2, v6, s4
	v_lshl_add_u32 v2, s20, 6, v2
	v_or_b32_e32 v2, v2, v3
	v_mov_b64_e32 v[4:5], s[12:13]
	s_or_b64 exec, exec, s[22:23]
	v_ashrrev_i32_e32 v3, 31, v2
	v_lshl_add_u64 v[2:3], v[2:3], 2, v[4:5]
	flat_load_dword v2, v[2:3]
	v_lshl_add_u32 v3, v1, 2, v254
	v_mov_b32_e32 v1, v170
	s_waitcnt vmcnt(0) lgkmcnt(0)
	ds_write_b32 v3, v2
	s_nop 0
	v_ashrrev_i32_e32 v2, 9, v1
	v_add_u32_e32 v2, s46, v2
	v_cmp_lt_i32_e32 vcc, s91, v2
	s_and_saveexec_b64 s[4:5], vcc
	s_xor_b64 s[22:23], exec, s[4:5]
	v_add_u32_e32 v2, 0xfffffef0, v2
	v_mul_hi_u32 v3, v2, s96
	v_lshrrev_b32_e32 v3, 3, v3
	v_add_u32_e32 v4, 16, v3
	v_lshl_add_u32 v3, v3, 5, v3
	v_sub_u32_e32 v13, v2, v3
	s_andn2_saveexec_b64 s[22:23], s[22:23]
	v_mul_hi_i32 v3, v2, s97
	v_lshrrev_b32_e32 v4, 31, v3
	v_ashrrev_i32_e32 v3, 3, v3
	v_add_u32_e32 v4, v3, v4
	v_lshl_add_u32 v3, v4, 4, v4
	v_sub_u32_e32 v13, v2, v3
	s_or_b64 exec, exec, s[22:23]
	v_cmp_lt_i32_e32 vcc, 15, v4
	s_and_saveexec_b64 s[4:5], vcc
	s_xor_b64 s[4:5], exec, s[4:5]
	v_add_u32_e32 v2, -16, v4
	v_mov_b32_e32 v3, v0
	v_lshlrev_b64 v[2:3], 12, v[2:3]
	v_lshl_add_u64 v[2:3], v[2:3], 0, s[42:43]
	s_andn2_saveexec_b64 s[22:23], s[4:5]
	v_ashrrev_i32_e32 v5, 31, v4
	v_lshlrev_b64 v[2:3], 11, v[4:5]
	s_or_b64 exec, exec, s[22:23]
	v_lshlrev_b32_e32 v142, 4, v1
	v_add_u32_e32 v12, 0x1000, v142
	v_ashrrev_i32_e32 v4, 13, v12
	v_add_u32_e32 v4, s46, v4
	v_cmp_lt_i32_e32 vcc, s91, v4
	s_and_saveexec_b64 s[4:5], vcc
	s_xor_b64 s[4:5], exec, s[4:5]
	v_add_u32_e32 v4, 0xfffffef0, v4
	v_mul_hi_u32 v5, v4, s96
	v_lshrrev_b32_e32 v5, 3, v5
	v_add_u32_e32 v6, 16, v5
	v_lshl_add_u32 v5, v5, 5, v5
	v_sub_u32_e32 v15, v4, v5
	s_andn2_saveexec_b64 s[22:23], s[4:5]
	v_mul_hi_i32 v5, v4, s97
	v_lshrrev_b32_e32 v6, 31, v5
	v_ashrrev_i32_e32 v5, 3, v5
	v_add_u32_e32 v6, v5, v6
	v_lshl_add_u32 v5, v6, 4, v6
	v_sub_u32_e32 v15, v4, v5
	s_or_b64 exec, exec, s[22:23]
	v_cmp_lt_i32_e32 vcc, 15, v6
	s_and_saveexec_b64 s[4:5], vcc
	s_xor_b64 s[4:5], exec, s[4:5]
	v_add_u32_e32 v4, -16, v6
	v_mov_b32_e32 v5, v0
	v_lshlrev_b64 v[4:5], 12, v[4:5]
	v_lshl_add_u64 v[4:5], v[4:5], 0, s[42:43]
	s_andn2_saveexec_b64 s[4:5], s[4:5]
	v_ashrrev_i32_e32 v7, 31, v6
	v_lshlrev_b64 v[4:5], 11, v[6:7]
	s_or_b64 exec, exec, s[4:5]
	v_add_u32_e32 v14, 0x2000, v142
	v_ashrrev_i32_e32 v6, 13, v14
	v_add_u32_e32 v6, s46, v6
	v_cmp_lt_i32_e32 vcc, s91, v6
	s_and_saveexec_b64 s[4:5], vcc
	s_xor_b64 s[4:5], exec, s[4:5]
	v_add_u32_e32 v6, 0xfffffef0, v6
	v_mul_hi_u32 v7, v6, s96
	v_lshrrev_b32_e32 v7, 3, v7
	v_add_u32_e32 v8, 16, v7
	v_lshl_add_u32 v7, v7, 5, v7
	v_sub_u32_e32 v17, v6, v7
	s_andn2_saveexec_b64 s[22:23], s[4:5]
	v_mul_hi_i32 v7, v6, s97
	v_lshrrev_b32_e32 v8, 31, v7
	v_ashrrev_i32_e32 v7, 3, v7
	v_add_u32_e32 v8, v7, v8
	v_lshl_add_u32 v7, v8, 4, v8
	v_sub_u32_e32 v17, v6, v7
	s_or_b64 exec, exec, s[22:23]
	v_cmp_lt_i32_e32 vcc, 15, v8
	s_and_saveexec_b64 s[4:5], vcc
	s_xor_b64 s[4:5], exec, s[4:5]
	v_add_u32_e32 v6, -16, v8
	v_mov_b32_e32 v7, v0
	v_lshlrev_b64 v[6:7], 12, v[6:7]
	v_lshl_add_u64 v[6:7], v[6:7], 0, s[42:43]
	s_andn2_saveexec_b64 s[4:5], s[4:5]
	v_ashrrev_i32_e32 v9, 31, v8
	v_lshlrev_b64 v[6:7], 11, v[8:9]
	s_or_b64 exec, exec, s[4:5]
	v_add_u32_e32 v16, 0x3000, v142
	v_ashrrev_i32_e32 v8, 13, v16
	v_add_u32_e32 v8, s46, v8
	v_cmp_lt_i32_e32 vcc, s91, v8
	s_and_saveexec_b64 s[4:5], vcc
	s_xor_b64 s[4:5], exec, s[4:5]
	v_add_u32_e32 v8, 0xfffffef0, v8
	v_mul_hi_u32 v9, v8, s96
	v_lshrrev_b32_e32 v9, 3, v9
	v_add_u32_e32 v10, 16, v9
	v_lshl_add_u32 v9, v9, 5, v9
	v_sub_u32_e32 v18, v8, v9
	s_andn2_saveexec_b64 s[22:23], s[4:5]
	v_mul_hi_i32 v9, v8, s97
	v_lshrrev_b32_e32 v10, 31, v9
	v_ashrrev_i32_e32 v9, 3, v9
	v_add_u32_e32 v10, v9, v10
	v_lshl_add_u32 v9, v10, 4, v10
	v_sub_u32_e32 v18, v8, v9
	s_or_b64 exec, exec, s[22:23]
	v_cmp_lt_i32_e32 vcc, 15, v10
	s_and_saveexec_b64 s[4:5], vcc
	s_xor_b64 s[4:5], exec, s[4:5]
	v_add_u32_e32 v8, -16, v10
	v_mov_b32_e32 v9, v0
	v_lshlrev_b64 v[8:9], 12, v[8:9]
	v_lshl_add_u64 v[8:9], v[8:9], 0, s[42:43]
	s_andn2_saveexec_b64 s[4:5], s[4:5]
	v_ashrrev_i32_e32 v11, 31, v10
	v_lshlrev_b64 v[8:9], 11, v[10:11]
	s_or_b64 exec, exec, s[4:5]
	v_mad_u64_u32 v[24:25], s[4:5], v17, s54, -1
	v_bfe_u32 v22, v142, 6, 7
	v_mov_b32_e32 v23, v0
	v_ashrrev_i32_e32 v25, 31, v24
	v_lshl_add_u64 v[24:25], v[24:25], 0, v[22:23]
	v_lshl_add_u64 v[6:7], v[24:25], 0, v[6:7]
	v_cmp_lt_i64_e32 vcc, 0, v[6:7]
	v_and_b32_e32 v44, 32, v1
	v_bitop3_b32 v10, v142, v44, 48 bitop3:0x6c
	v_cndmask_b32_e32 v7, 0, v7, vcc
	v_cndmask_b32_e32 v6, 0, v6, vcc
	v_cmp_gt_i64_e32 vcc, s[44:45], v[6:7]
	v_mov_b32_e32 v11, v0
	v_lshl_add_u64 v[20:21], s[6:7], 0, v[10:11]
	v_cndmask_b32_e32 v6, v174, v6, vcc
	v_lshlrev_b32_e32 v6, 11, v6
	v_mov_b32_e32 v7, v0
	v_bfe_u32 v19, v142, 6, 4
	v_lshl_add_u64 v[24:25], v[20:21], 0, v[6:7]
	v_lshrrev_b32_e32 v7, 6, v16
	v_and_or_b32 v26, v7, s82, v19
	v_lshrrev_b32_e32 v7, 6, v12
	v_mad_u64_u32 v[30:31], s[24:25], v15, s54, -1
	v_and_or_b32 v28, v7, s82, v19
	v_ashrrev_i32_e32 v31, 31, v30
	v_mov_b32_e32 v29, v0
	v_lshl_add_u64 v[28:29], v[30:31], 0, v[28:29]
	v_lshl_add_u64 v[4:5], v[28:29], 0, v[4:5]
	v_mad_u64_u32 v[30:31], s[24:25], v13, s54, -1
	v_cmp_lt_i64_e32 vcc, 0, v[4:5]
	v_ashrrev_i32_e32 v31, 31, v30
	v_lshl_add_u64 v[22:23], v[30:31], 0, v[22:23]
	v_cndmask_b32_e32 v5, 0, v5, vcc
	v_cndmask_b32_e32 v4, 0, v4, vcc
	v_cmp_gt_i64_e32 vcc, s[44:45], v[4:5]
	v_lshl_add_u64 v[2:3], v[22:23], 0, v[2:3]
	v_mad_u64_u32 v[18:19], s[66:67], v18, s54, -1
	v_cndmask_b32_e32 v4, v174, v4, vcc
	v_cmp_lt_i64_e32 vcc, 0, v[2:3]
	v_ashrrev_i32_e32 v19, 31, v18
	v_mov_b32_e32 v27, v0
	v_cndmask_b32_e32 v3, 0, v3, vcc
	v_cndmask_b32_e32 v2, 0, v2, vcc
	v_lshl_add_u64 v[18:19], v[18:19], 0, v[26:27]
	v_cmp_gt_i64_e32 vcc, s[44:45], v[2:3]
	v_lshl_add_u64 v[8:9], v[18:19], 0, v[8:9]
	v_mov_b32_e32 v3, v0
	v_cndmask_b32_e32 v2, v174, v2, vcc
	v_cmp_lt_i64_e32 vcc, 0, v[8:9]
	v_lshlrev_b32_e32 v2, 11, v2
	v_lshl_add_u64 v[22:23], v[20:21], 0, v[2:3]
	v_cndmask_b32_e32 v9, 0, v9, vcc
	v_cndmask_b32_e32 v8, 0, v8, vcc
	v_cmp_gt_i64_e32 vcc, s[44:45], v[8:9]
	s_ashr_i32 s21, s20, 31
	v_readfirstlane_b32 s5, v142
	v_cndmask_b32_e32 v3, v174, v8, vcc
	v_lshrrev_b32_e32 v32, 6, v142
	v_lshlrev_b32_e32 v4, 11, v4
	v_mov_b32_e32 v5, v0
	s_lshl_b64 s[24:25], s[20:21], 18
	v_lshlrev_b32_e32 v8, 11, v3
	v_mov_b32_e32 v9, v0
	v_ashrrev_i32_e32 v3, 2, v1
	s_waitcnt vmcnt(0)
	s_mov_b32 m0, s5
	v_readfirstlane_b32 s5, v12
	v_lshl_add_u64 v[28:29], v[20:21], 0, v[4:5]
	s_add_u32 s64, s26, s24
	v_lshl_add_u64 v[18:19], v[20:21], 0, v[8:9]
	v_bfi_b32 v20, 15, v32, v3
	v_ashrrev_i32_e32 v3, 6, v12
	s_mov_b32 m0, s5
	v_readfirstlane_b32 s5, v14
	s_addc_u32 s65, s27, s25
	v_ashrrev_i32_e32 v21, 31, v20
	v_bfi_b32 v30, -16, v3, v32
	v_add_u32_e32 v15, 0x4000, v142
	s_mov_b32 m0, s5
	v_readfirstlane_b32 s5, v16
	v_lshl_add_u64 v[10:11], s[64:65], 0, v[10:11]
	v_lshlrev_b64 v[20:21], 11, v[20:21]
	v_ashrrev_i32_e32 v31, 31, v30
	v_add_u32_e32 v17, 0x5000, v142
	s_mov_b32 m0, s5
	v_readfirstlane_b32 s5, v15
	v_lshl_add_u64 v[26:27], v[10:11], 0, v[20:21]
	v_lshlrev_b64 v[30:31], 11, v[30:31]
	v_add_u32_e32 v46, 0x6000, v142
	s_mov_b32 m0, s5
	v_readfirstlane_b32 s5, v17
	v_lshl_add_u64 v[10:11], v[10:11], 0, v[30:31]
	v_add_u32_e32 v47, 0x7000, v142
	s_mov_b32 m0, s5
	v_readfirstlane_b32 s5, v46
	v_lshl_add_u64 v[32:33], v[22:23], 0, 64
	v_add_u32_e32 v48, 0x8000, v142
	s_mov_b32 m0, s5
	v_readfirstlane_b32 s5, v47
	v_add_u32_e32 v49, 0x9000, v142
	v_lshl_add_u64 v[34:35], v[28:29], 0, 64
	s_mov_b32 m0, s5
	v_readfirstlane_b32 s5, v48
	v_add_u32_e32 v50, 0xa000, v142
	v_lshl_add_u64 v[36:37], v[24:25], 0, 64
	s_mov_b32 m0, s5
	v_readfirstlane_b32 s5, v49
	v_add_u32_e32 v51, 0xb000, v142
	v_lshl_add_u64 v[38:39], v[18:19], 0, 64
	s_mov_b32 m0, s5
	v_readfirstlane_b32 s5, v50
	v_lshl_add_u64 v[40:41], v[26:27], 0, 64
	s_mov_b32 m0, s5
	v_readfirstlane_b32 s5, v51
	v_lshl_add_u64 v[42:43], v[10:11], 0, 64
	s_mov_b32 m0, s5
	v_and_b32_e32 v45, 48, v142
	v_and_b32_e32 v143, 15, v1
	v_bfe_u32 v144, v1, 4, 2
	v_lshlrev_b32_e32 v5, 6, v1
	v_lshlrev_b32_e32 v13, 2, v1
	v_lshl_add_u64 v[10:11], s[24:25], 0, v[30:31]
	v_lshlrev_b32_e32 v3, 4, v144
	v_and_b32_e32 v7, 0x3c0, v5
	v_lshlrev_b32_e32 v9, 6, v143
	v_and_b32_e32 v13, 32, v13
	v_bitop3_b32 v10, v10, v45, v44 bitop3:0xf6
	v_bitop3_b32 v149, v3, v13, v7 bitop3:0x36
	v_bitop3_b32 v145, v3, v13, v9 bitop3:0x36
	v_lshl_add_u64 v[130:131], s[16:17], 0, v[10:11]
	v_lshl_add_u64 v[10:11], s[24:25], 0, v[20:21]
	v_bitop3_b32 v2, v2, v45, v44 bitop3:0xf6
	v_mov_b32_e32 v3, v0
	v_and_b32_e32 v147, 0xfffff000, v5
	v_bitop3_b32 v10, v10, v45, v44 bitop3:0xf6
	v_bitop3_b32 v8, v8, v45, v44 bitop3:0xf6
	v_mov_b32_e32 v9, v0
	v_bitop3_b32 v6, v6, v45, v44 bitop3:0xf6
	v_mov_b32_e32 v7, v0
	v_bitop3_b32 v4, v4, v45, v44 bitop3:0xf6
	v_mov_b32_e32 v5, v0
	v_lshl_add_u64 v[140:141], s[18:19], 0, v[2:3]
	v_mov_b32_e32 v2, 0
	s_mov_b64 s[22:23], 0
	s_mov_b32 s4, 0
	v_lshl_add_u64 v[132:133], s[16:17], 0, v[10:11]
	v_lshl_add_u64 v[134:135], s[18:19], 0, v[8:9]
	v_lshl_add_u64 v[136:137], s[18:19], 0, v[6:7]
	v_lshl_add_u64 v[138:139], s[18:19], 0, v[4:5]
	v_mov_b32_e32 v3, v2
	v_mov_b32_e32 v4, v2
	v_mov_b32_e32 v5, v2
	v_mov_b32_e32 v6, v2
	v_mov_b32_e32 v7, v2
	v_mov_b32_e32 v8, v2
	v_mov_b32_e32 v9, v2
	v_mov_b32_e32 v10, v2
	v_mov_b32_e32 v11, v2
	v_mov_b32_e32 v12, v2
	v_mov_b32_e32 v13, v2
	v_mov_b32_e32 v18, v2
	v_mov_b32_e32 v19, v2
	v_mov_b32_e32 v20, v2
	v_mov_b32_e32 v21, v2
	v_mov_b32_e32 v26, v2
	v_mov_b32_e32 v27, v2
	v_mov_b32_e32 v28, v2
	v_mov_b32_e32 v29, v2
	v_mov_b32_e32 v38, v2
	v_mov_b32_e32 v39, v2
	v_mov_b32_e32 v40, v2
	v_mov_b32_e32 v41, v2
	v_mov_b32_e32 v46, v2
	v_mov_b32_e32 v47, v2
	v_mov_b32_e32 v48, v2
	v_mov_b32_e32 v49, v2
	v_mov_b32_e32 v62, v2
	v_mov_b32_e32 v63, v2
	v_mov_b32_e32 v64, v2
	v_mov_b32_e32 v65, v2
	v_mov_b32_e32 v14, v2
	v_mov_b32_e32 v15, v2
	v_mov_b32_e32 v16, v2
	v_mov_b32_e32 v17, v2
	v_mov_b32_e32 v22, v2
	v_mov_b32_e32 v23, v2
	v_mov_b32_e32 v24, v2
	v_mov_b32_e32 v25, v2
	v_mov_b32_e32 v30, v2
	v_mov_b32_e32 v31, v2
	v_mov_b32_e32 v32, v2
	v_mov_b32_e32 v33, v2
	v_mov_b32_e32 v42, v2
	v_mov_b32_e32 v43, v2
	v_mov_b32_e32 v44, v2
	v_mov_b32_e32 v45, v2
	v_mov_b32_e32 v54, v2
	v_mov_b32_e32 v55, v2
	v_mov_b32_e32 v56, v2
	v_mov_b32_e32 v57, v2
	v_mov_b32_e32 v70, v2
	v_mov_b32_e32 v71, v2
	v_mov_b32_e32 v72, v2
	v_mov_b32_e32 v73, v2
	v_mov_b32_e32 v78, v2
	v_mov_b32_e32 v79, v2
	v_mov_b32_e32 v80, v2
	v_mov_b32_e32 v81, v2
	v_mov_b32_e32 v94, v2
	v_mov_b32_e32 v95, v2
	v_mov_b32_e32 v96, v2
	v_mov_b32_e32 v97, v2
	v_mov_b32_e32 v34, v2
	v_mov_b32_e32 v35, v2
	v_mov_b32_e32 v36, v2
	v_mov_b32_e32 v37, v2
	v_mov_b32_e32 v50, v2
	v_mov_b32_e32 v51, v2
	v_mov_b32_e32 v52, v2
	v_mov_b32_e32 v53, v2
	v_mov_b32_e32 v58, v2
	v_mov_b32_e32 v59, v2
	v_mov_b32_e32 v60, v2
	v_mov_b32_e32 v61, v2
	v_mov_b32_e32 v74, v2
	v_mov_b32_e32 v75, v2
	v_mov_b32_e32 v76, v2
	v_mov_b32_e32 v77, v2
	v_mov_b32_e32 v86, v2
	v_mov_b32_e32 v87, v2
	v_mov_b32_e32 v88, v2
	v_mov_b32_e32 v89, v2
	v_mov_b32_e32 v98, v2
	v_mov_b32_e32 v99, v2
	v_mov_b32_e32 v100, v2
	v_mov_b32_e32 v101, v2
	v_mov_b32_e32 v106, v2
	v_mov_b32_e32 v107, v2
	v_mov_b32_e32 v108, v2
	v_mov_b32_e32 v109, v2
	v_mov_b32_e32 v114, v2
	v_mov_b32_e32 v115, v2
	v_mov_b32_e32 v116, v2
	v_mov_b32_e32 v117, v2
	v_mov_b32_e32 v66, v2
	v_mov_b32_e32 v67, v2
	v_mov_b32_e32 v68, v2
	v_mov_b32_e32 v69, v2
	v_mov_b32_e32 v82, v2
	v_mov_b32_e32 v83, v2
	v_mov_b32_e32 v84, v2
	v_mov_b32_e32 v85, v2
	v_mov_b32_e32 v90, v2
	v_mov_b32_e32 v91, v2
	v_mov_b32_e32 v92, v2
	v_mov_b32_e32 v93, v2
	v_mov_b32_e32 v102, v2
	v_mov_b32_e32 v103, v2
	v_mov_b32_e32 v104, v2
	v_mov_b32_e32 v105, v2
	v_mov_b32_e32 v110, v2
	v_mov_b32_e32 v111, v2
	v_mov_b32_e32 v112, v2
	v_mov_b32_e32 v113, v2
	v_mov_b32_e32 v118, v2
	v_mov_b32_e32 v119, v2
	v_mov_b32_e32 v120, v2
	v_mov_b32_e32 v121, v2
	v_mov_b32_e32 v122, v2
	v_mov_b32_e32 v123, v2
	v_mov_b32_e32 v124, v2
	v_mov_b32_e32 v125, v2
	v_mov_b32_e32 v126, v2
	v_mov_b32_e32 v127, v2
	v_mov_b32_e32 v128, v2
	v_mov_b32_e32 v129, v2
	s_and_b32 s32, s2, 7
	s_lshl_b32 s32, s32, 2
	s_add_u32 s4, s28, s32
	s_addc_u32 s5, s29, 0
	v_mov_b32_e32 v154, s4
	v_mov_b32_e32 v155, s5
	v_cmp_eq_u32_e32 vcc, 0, v170
	s_and_saveexec_b64 s[4:5], vcc
	global_atomic_add v253, v[154:155], v171, off sc0
	s_mov_b64 exec, s[4:5]
	v_and_b32_e32 v154, 63, v170
	v_lshrrev_b32_e32 v155, 3, v154
	v_and_b32_e32 v156, 7, v154
	v_xor_b32_e32 v156, v156, v155
	v_lshrrev_b32_e32 v157, 6, v170
	v_lshlrev_b32_e32 v231, 4, v156
	v_lshrrev_b32_e32 v159, 1, v157
	v_add_u32_e32 v159, s46, v159
	v_mul_u32_u24_e32 v160, 0xf10, v159
	v_lshrrev_b32_e32 v160, 16, v160
	v_mul_u32_u24_e32 v161, 17, v160
	v_sub_u32_e32 v161, v159, v161
	v_lshlrev_b32_e32 v160, 11, v160
	v_mul_u32_u24_e32 v161, 0x7e, v161
	v_add_u32_e32 v160, v160, v161
	v_add_u32_e32 v161, 0xfffffef0, v159
	v_mul_u32_u24_e32 v162, 0x7c2, v161
	v_lshrrev_b32_e32 v162, 16, v162
	v_mul_u32_u24_e32 v224, 33, v162
	v_sub_u32_e32 v161, v161, v224
	v_lshlrev_b32_e32 v162, 12, v162
	v_mul_u32_u24_e32 v161, 0x7e, v161
	v_add_u32_e32 v161, v162, v161
	v_add_u32_e32 v161, 0x8000, v161
	v_cmp_lt_u32_e32 vcc, 0x10f, v159
	s_nop 1
	v_cndmask_b32_e32 v160, v160, v161, vcc
	v_and_b32_e32 v161, 1, v157
	v_lshl_add_u32 v161, v161, 6, v155
	v_add3_u32 v224, v160, v161, -1
	v_lshl_add_u32 v158, v157, 5, v155
	v_mul_u32_u24_e32 v225, 0x800, v158
	v_lshl_add_u32 v225, v156, 4, v225
	v_and_b32_e32 v155, 15, v154
	v_lshrrev_b32_e32 v156, 4, v154
	v_and_b32_e32 v158, 7, v155
	v_xor_b32_e32 v156, v156, v158
	v_lshlrev_b32_e32 v156, 4, v156
	v_lshl_add_u32 v229, v155, 7, v156
	v_lshl_add_u32 v227, v157, 13, v229
	v_xor_b32_e32 v228, 64, v227
	v_add_u32_e32 v229, 0x8000, v229
	v_xor_b32_e32 v230, 64, v229
	s_mov_b32 s4, s6
	s_mov_b32 s5, s7
	s_mov_b32 s22, s64
	s_mov_b32 s23, s65
	s_mov_b32 s21, 0
	v_readfirstlane_b32 s32, v142
	s_lshl_b32 m0, s32, 3
	v_add_u32_e32 v226, 0, v224
	v_max_i32_e32 v226, 0, v226
	v_min_i32_e32 v226, 0xffff, v226
	v_lshl_add_u32 v226, v226, 11, v231
	global_load_lds_dwordx4 v226, s[4:5]
	s_add_u32 m0, m0, 0x400
	v_add_u32_e32 v226, 8, v224
	v_max_i32_e32 v226, 0, v226
	v_min_i32_e32 v226, 0xffff, v226
	v_lshl_add_u32 v226, v226, 11, v231
	global_load_lds_dwordx4 v226, s[4:5]
	s_add_u32 m0, m0, 0x400
	v_add_u32_e32 v226, 16, v224
	v_max_i32_e32 v226, 0, v226
	v_min_i32_e32 v226, 0xffff, v226
	v_lshl_add_u32 v226, v226, 11, v231
	global_load_lds_dwordx4 v226, s[4:5]
	s_add_u32 m0, m0, 0x400
	v_add_u32_e32 v226, 24, v224
	v_max_i32_e32 v226, 0, v226
	v_min_i32_e32 v226, 0xffff, v226
	v_lshl_add_u32 v226, v226, 11, v231
	global_load_lds_dwordx4 v226, s[4:5]
	s_add_u32 m0, m0, 0x400
	v_add_u32_e32 v226, 32, v224
	v_max_i32_e32 v226, 0, v226
	v_min_i32_e32 v226, 0xffff, v226
	v_lshl_add_u32 v226, v226, 11, v231
	global_load_lds_dwordx4 v226, s[4:5]
	s_add_u32 m0, m0, 0x400
	v_add_u32_e32 v226, 40, v224
	v_max_i32_e32 v226, 0, v226
	v_min_i32_e32 v226, 0xffff, v226
	v_lshl_add_u32 v226, v226, 11, v231
	global_load_lds_dwordx4 v226, s[4:5]
	s_add_u32 m0, m0, 0x400
	v_add_u32_e32 v226, 48, v224
	v_max_i32_e32 v226, 0, v226
	v_min_i32_e32 v226, 0xffff, v226
	v_lshl_add_u32 v226, v226, 11, v231
	global_load_lds_dwordx4 v226, s[4:5]
	s_add_u32 m0, m0, 0x400
	v_add_u32_e32 v226, 56, v224
	v_max_i32_e32 v226, 0, v226
	v_min_i32_e32 v226, 0xffff, v226
	v_lshl_add_u32 v226, v226, 11, v231
	global_load_lds_dwordx4 v226, s[4:5]
	v_readfirstlane_b32 s32, v142
	s_lshl_b32 s32, s32, 2
	s_add_u32 m0, s32, 0x8000
	v_mov_b32_e32 v226, v225
	global_load_lds_dwordx4 v226, s[22:23]
	s_add_u32 m0, m0, 0x400
	v_add_u32_e32 v226, 0x4000, v225
	global_load_lds_dwordx4 v226, s[22:23]
	s_add_u32 m0, m0, 0x400
	v_add_u32_e32 v226, 0x8000, v225
	global_load_lds_dwordx4 v226, s[22:23]
	s_add_u32 m0, m0, 0x400
	v_add_u32_e32 v226, 0xc000, v225
	global_load_lds_dwordx4 v226, s[22:23]

.LBB0_523:
	s_mov_b32 s4, s2
	s_and_b32 s18, s4, 7
	s_cmp_lg_u32 s24, 0
	s_waitcnt lgkmcnt(0)
	s_barrier
	s_cbranch_scc0 .LBB0_532
	v_mov_b32_e32 v1, v170
	s_nop 0
	v_cmp_eq_u32_e32 vcc, 0, v1
	s_and_saveexec_b64 s[16:17], vcc
	s_cbranch_execz .LBB0_526
	s_mov_b32 s4, s34
	s_ashr_i32 s19, s4, 3
	s_lshl_b32 s4, s18, 2
	s_add_u32 s4, s22, s4
	s_addc_u32 s5, s23, 0
	v_mov_b64_e32 v[2:3], s[4:5]
	v_mov_b32_e32 v1, v253
	s_mov_b64 s[4:5], src_shared_base
	v_mov_b32_e32 v147, s5
	s_waitcnt vmcnt(0) lgkmcnt(0)
	v_add_u32_e32 v1, s19, v1
	flat_store_dword v[146:147], v1 sc0 sc1
	s_waitcnt vmcnt(0)

.LBB0_528:
	s_cmpk_gt_i32 s16, 0xff
	s_mov_b64 s[4:5], -1
	s_cbranch_scc1 .LBB0_522
	s_ashr_i32 s4, s16, 31
	s_lshr_b32 s4, s4, 26
	s_add_i32 s4, s16, s4
	s_andn2_b32 s4, s4, 63
	s_sub_i32 s5, s16, s4
	s_ashr_i32 s16, s5, 3
	s_lshl_b32 s5, s5, 3
	s_and_b32 s5, s5, 56
	s_or_b32 s4, s4, s5
	v_mov_b32_e32 v1, v170
	s_barrier
	s_or_b32 s4, s4, s18
	s_lshl_b32 s4, s4, 8
	v_lshlrev_b32_e32 v145, 4, v1
	v_bfe_u32 v35, v1, 2, 4
	v_ashrrev_i32_e32 v14, 2, v1
	v_add_u32_e32 v37, 0x1000, v145
	v_add_u32_e32 v38, 0x2000, v145
	v_add_u32_e32 v40, 0x3000, v145
	v_or_b32_e32 v12, s4, v35
	v_and_b32_e32 v6, -16, v14
	v_ashrrev_i32_e32 v19, 6, v37
	v_ashrrev_i32_e32 v10, 6, v38
	v_ashrrev_i32_e32 v13, 6, v40
	v_and_b32_e32 v34, 32, v1
	v_add_u32_e32 v6, v12, v6
	v_and_b32_e32 v8, -16, v19
	v_and_b32_e32 v39, -16, v10
	v_and_b32_e32 v41, -16, v13
	v_bitop3_b32 v2, v145, v34, 48 bitop3:0x6c
	v_mov_b32_e32 v3, v0
	v_ashrrev_i32_e32 v7, 31, v6
	v_add_u32_e32 v8, v8, v12
	v_add_u32_e32 v10, v39, v12
	v_add_u32_e32 v12, v41, v12
	s_ashr_i32 s17, s16, 31
	v_lshl_add_u64 v[4:5], s[36:37], 0, v[2:3]
	v_lshlrev_b64 v[6:7], 11, v[6:7]
	v_ashrrev_i32_e32 v9, 31, v8
	v_ashrrev_i32_e32 v11, 31, v10
	v_ashrrev_i32_e32 v13, 31, v12
	v_readfirstlane_b32 s5, v145
	s_lshl_b64 s[18:19], s[16:17], 18
	v_lshrrev_b32_e32 v18, 2, v1
	v_lshl_add_u64 v[6:7], v[4:5], 0, v[6:7]
	v_lshlrev_b64 v[8:9], 11, v[8:9]
	v_lshlrev_b64 v[10:11], 11, v[10:11]
	v_lshlrev_b64 v[12:13], 11, v[12:13]
	s_waitcnt vmcnt(0)
	s_mov_b32 m0, s5
	v_readfirstlane_b32 s5, v37
	s_add_u32 s26, s20, s18
	v_lshl_add_u64 v[8:9], v[4:5], 0, v[8:9]
	v_lshl_add_u64 v[10:11], v[4:5], 0, v[10:11]
	v_lshl_add_u64 v[4:5], v[4:5], 0, v[12:13]
	v_bfi_b32 v12, 15, v18, v14
	s_mov_b32 m0, s5
	v_readfirstlane_b32 s5, v38
	s_addc_u32 s27, s21, s19
	v_ashrrev_i32_e32 v13, 31, v12
	v_bfi_b32 v18, -16, v19, v18
	v_add_u32_e32 v42, 0x4000, v145
	s_mov_b32 m0, s5
	v_readfirstlane_b32 s5, v40
	v_lshl_add_u64 v[2:3], s[26:27], 0, v[2:3]
	v_lshlrev_b64 v[14:15], 11, v[12:13]
	v_ashrrev_i32_e32 v19, 31, v18
	v_add_u32_e32 v43, 0x5000, v145
	s_mov_b32 m0, s5
	v_readfirstlane_b32 s5, v42
	v_lshl_add_u64 v[16:17], v[2:3], 0, v[14:15]
	v_lshlrev_b64 v[20:21], 11, v[18:19]
	v_add_u32_e32 v44, 0x6000, v145
	s_mov_b32 m0, s5
	v_readfirstlane_b32 s5, v43
	v_and_b32_e32 v142, 15, v1
	v_lshl_add_u64 v[2:3], v[2:3], 0, v[20:21]
	v_bfe_u32 v143, v1, 4, 2
	v_lshlrev_b32_e32 v19, 6, v1
	v_lshlrev_b32_e32 v22, 2, v1
	v_add_u32_e32 v45, 0x7000, v145
	s_mov_b32 m0, s5
	v_readfirstlane_b32 s5, v44
	v_lshlrev_b32_e32 v13, 4, v143
	v_and_b32_e32 v24, 0x3c0, v19
	v_lshlrev_b32_e32 v25, 6, v142
	v_and_b32_e32 v26, 32, v22
	v_lshl_add_u64 v[22:23], v[6:7], 0, 64
	v_add_u32_e32 v46, 0x8000, v145
	s_mov_b32 m0, s5
	v_readfirstlane_b32 s5, v45
	v_add_u32_e32 v47, 0x9000, v145
	v_bitop3_b32 v149, v13, v26, v24 bitop3:0x36
	v_bitop3_b32 v144, v13, v26, v25 bitop3:0x36
	v_lshl_add_u64 v[24:25], v[8:9], 0, 64
	s_mov_b32 m0, s5
	v_readfirstlane_b32 s5, v46
	v_add_u32_e32 v48, 0xa000, v145
	v_lshl_add_u64 v[26:27], v[10:11], 0, 64
	s_mov_b32 m0, s5
	v_readfirstlane_b32 s5, v47
	v_add_u32_e32 v49, 0xb000, v145
	v_lshl_add_u64 v[28:29], v[4:5], 0, 64
	s_mov_b32 m0, s5
	v_readfirstlane_b32 s5, v48
	v_lshl_add_u64 v[30:31], v[16:17], 0, 64
	s_mov_b32 m0, s5
	v_readfirstlane_b32 s5, v49
	v_lshl_add_u64 v[32:33], v[2:3], 0, 64
	s_mov_b32 m0, s5
	v_and_b32_e32 v36, 48, v145
	v_lshl_add_u64 v[2:3], s[18:19], 0, v[20:21]
	v_bitop3_b32 v2, v2, v36, v34 bitop3:0xf6
	v_lshl_add_u64 v[130:131], s[12:13], 0, v[2:3]
	v_lshl_add_u64 v[2:3], s[18:19], 0, v[14:15]
	v_bitop3_b32 v2, v2, v36, v34 bitop3:0xf6
	v_lshl_add_u64 v[132:133], s[12:13], 0, v[2:3]
	v_add_u32_e32 v2, s4, v41
	v_or_b32_e32 v2, v2, v35
	v_ashrrev_i32_e32 v3, 31, v2
	v_lshlrev_b64 v[2:3], 11, v[2:3]
	v_bitop3_b32 v2, v2, v36, v34 bitop3:0xf6
	v_lshl_add_u64 v[134:135], s[14:15], 0, v[2:3]
	v_add_u32_e32 v2, s4, v39
	v_or_b32_e32 v2, v2, v35
	v_ashrrev_i32_e32 v3, 31, v2
	v_lshlrev_b64 v[2:3], 11, v[2:3]
	v_bitop3_b32 v2, v2, v36, v34 bitop3:0xf6
	v_lshl_add_u64 v[136:137], s[14:15], 0, v[2:3]
	v_add_u32_e32 v2, s4, v18
	v_ashrrev_i32_e32 v3, 31, v2
	v_lshlrev_b64 v[2:3], 11, v[2:3]
	v_bitop3_b32 v2, v2, v36, v34 bitop3:0xf6
	v_lshl_add_u64 v[138:139], s[14:15], 0, v[2:3]
	v_add_u32_e32 v2, s4, v12
	v_ashrrev_i32_e32 v3, 31, v2
	v_lshlrev_b64 v[2:3], 11, v[2:3]
	v_bitop3_b32 v2, v2, v36, v34 bitop3:0xf6
	v_lshl_add_u64 v[140:141], s[14:15], 0, v[2:3]
	v_mov_b32_e32 v2, 0
	v_and_b32_e32 v147, 0xfffff000, v19
	s_mov_b32 s5, 0
	s_mov_b64 s[18:19], 0
	v_mov_b32_e32 v3, v2
	v_mov_b32_e32 v4, v2
	v_mov_b32_e32 v5, v2
	v_mov_b32_e32 v6, v2
	v_mov_b32_e32 v7, v2
	v_mov_b32_e32 v8, v2
	v_mov_b32_e32 v9, v2
	v_mov_b32_e32 v10, v2
	v_mov_b32_e32 v11, v2
	v_mov_b32_e32 v12, v2
	v_mov_b32_e32 v13, v2
	v_mov_b32_e32 v14, v2
	v_mov_b32_e32 v15, v2
	v_mov_b32_e32 v16, v2
	v_mov_b32_e32 v17, v2
	v_mov_b32_e32 v18, v2
	v_mov_b32_e32 v19, v2
	v_mov_b32_e32 v20, v2
	v_mov_b32_e32 v21, v2
	v_mov_b32_e32 v26, v2
	v_mov_b32_e32 v27, v2
	v_mov_b32_e32 v28, v2
	v_mov_b32_e32 v29, v2
	v_mov_b32_e32 v38, v2
	v_mov_b32_e32 v39, v2
	v_mov_b32_e32 v40, v2
	v_mov_b32_e32 v41, v2
	v_mov_b32_e32 v54, v2
	v_mov_b32_e32 v55, v2
	v_mov_b32_e32 v56, v2
	v_mov_b32_e32 v57, v2
	v_mov_b32_e32 v22, v2
	v_mov_b32_e32 v23, v2
	v_mov_b32_e32 v24, v2
	v_mov_b32_e32 v25, v2
	v_mov_b32_e32 v30, v2
	v_mov_b32_e32 v31, v2
	v_mov_b32_e32 v32, v2
	v_mov_b32_e32 v33, v2
	v_mov_b32_e32 v34, v2
	v_mov_b32_e32 v35, v2
	v_mov_b32_e32 v36, v2
	v_mov_b32_e32 v37, v2
	v_mov_b32_e32 v42, v2
	v_mov_b32_e32 v43, v2
	v_mov_b32_e32 v44, v2
	v_mov_b32_e32 v45, v2
	v_mov_b32_e32 v46, v2
	v_mov_b32_e32 v47, v2
	v_mov_b32_e32 v48, v2
	v_mov_b32_e32 v49, v2
	v_mov_b32_e32 v58, v2
	v_mov_b32_e32 v59, v2
	v_mov_b32_e32 v60, v2
	v_mov_b32_e32 v61, v2
	v_mov_b32_e32 v70, v2
	v_mov_b32_e32 v71, v2
	v_mov_b32_e32 v72, v2
	v_mov_b32_e32 v73, v2
	v_mov_b32_e32 v86, v2
	v_mov_b32_e32 v87, v2
	v_mov_b32_e32 v88, v2
	v_mov_b32_e32 v89, v2
	v_mov_b32_e32 v50, v2
	v_mov_b32_e32 v51, v2
	v_mov_b32_e32 v52, v2
	v_mov_b32_e32 v53, v2
	v_mov_b32_e32 v62, v2
	v_mov_b32_e32 v63, v2
	v_mov_b32_e32 v64, v2
	v_mov_b32_e32 v65, v2
	v_mov_b32_e32 v66, v2
	v_mov_b32_e32 v67, v2
	v_mov_b32_e32 v68, v2
	v_mov_b32_e32 v69, v2
	v_mov_b32_e32 v74, v2
	v_mov_b32_e32 v75, v2
	v_mov_b32_e32 v76, v2
	v_mov_b32_e32 v77, v2
	v_mov_b32_e32 v78, v2
	v_mov_b32_e32 v79, v2
	v_mov_b32_e32 v80, v2
	v_mov_b32_e32 v81, v2
	v_mov_b32_e32 v90, v2
	v_mov_b32_e32 v91, v2
	v_mov_b32_e32 v92, v2
	v_mov_b32_e32 v93, v2
	v_mov_b32_e32 v102, v2
	v_mov_b32_e32 v103, v2
	v_mov_b32_e32 v104, v2
	v_mov_b32_e32 v105, v2
	v_mov_b32_e32 v114, v2
	v_mov_b32_e32 v115, v2
	v_mov_b32_e32 v116, v2
	v_mov_b32_e32 v117, v2
	v_mov_b32_e32 v82, v2
	v_mov_b32_e32 v83, v2
	v_mov_b32_e32 v84, v2
	v_mov_b32_e32 v85, v2
	v_mov_b32_e32 v94, v2
	v_mov_b32_e32 v95, v2
	v_mov_b32_e32 v96, v2
	v_mov_b32_e32 v97, v2
	v_mov_b32_e32 v98, v2
	v_mov_b32_e32 v99, v2
	v_mov_b32_e32 v100, v2
	v_mov_b32_e32 v101, v2
	v_mov_b32_e32 v106, v2
	v_mov_b32_e32 v107, v2
	v_mov_b32_e32 v108, v2
	v_mov_b32_e32 v109, v2
	v_mov_b32_e32 v110, v2
	v_mov_b32_e32 v111, v2
	v_mov_b32_e32 v112, v2
	v_mov_b32_e32 v113, v2
	v_mov_b32_e32 v118, v2
	v_mov_b32_e32 v119, v2
	v_mov_b32_e32 v120, v2
	v_mov_b32_e32 v121, v2
	v_mov_b32_e32 v122, v2
	v_mov_b32_e32 v123, v2
	v_mov_b32_e32 v124, v2
	v_mov_b32_e32 v125, v2
	v_mov_b32_e32 v126, v2
	v_mov_b32_e32 v127, v2
	v_mov_b32_e32 v128, v2
	v_mov_b32_e32 v129, v2
	s_and_b32 s32, s2, 7
	s_lshl_b32 s32, s32, 2
	s_add_u32 s18, s22, s32
	s_addc_u32 s19, s23, 0
	v_mov_b32_e32 v154, s18
	v_mov_b32_e32 v155, s19
	v_cmp_eq_u32_e32 vcc, 0, v170
	s_and_saveexec_b64 s[18:19], vcc
	global_atomic_add v253, v[154:155], v171, off sc0
	s_mov_b64 exec, s[18:19]
	v_and_b32_e32 v154, 63, v170
	v_lshrrev_b32_e32 v155, 3, v154
	v_and_b32_e32 v156, 7, v154
	v_xor_b32_e32 v156, v156, v155
	v_lshrrev_b32_e32 v157, 6, v170
	v_lshl_add_u32 v158, v157, 6, v155
	v_add_u32_e32 v158, s4, v158
	v_mul_u32_u24_e32 v224, 0x800, v158
	v_lshl_add_u32 v224, v156, 4, v224
	v_lshl_add_u32 v158, v157, 5, v155
	v_mul_u32_u24_e32 v225, 0x800, v158
	v_lshl_add_u32 v225, v156, 4, v225
	v_and_b32_e32 v155, 15, v154
	v_lshrrev_b32_e32 v156, 4, v154
	v_and_b32_e32 v158, 7, v155
	v_xor_b32_e32 v156, v156, v158
	v_lshlrev_b32_e32 v156, 4, v156
	v_lshl_add_u32 v229, v155, 7, v156
	v_lshl_add_u32 v227, v157, 13, v229
	v_xor_b32_e32 v228, 64, v227
	v_add_u32_e32 v229, 0x8000, v229
	v_xor_b32_e32 v230, 64, v229
	s_mov_b32 s18, s36
	s_mov_b32 s19, s37
	s_sub_u32 s32, s26, s36
	v_add_u32_e32 v225, s32, v225
	s_mov_b32 s25, 0
	v_readfirstlane_b32 s32, v145
	s_lshl_b32 m0, s32, 3
	v_mov_b32_e32 v226, v224
	global_load_lds_dwordx4 v226, s[18:19]
	s_add_u32 m0, m0, 0x400
	v_add_u32_e32 v226, 0x4000, v224
	global_load_lds_dwordx4 v226, s[18:19]
	s_add_u32 m0, m0, 0x400
	v_add_u32_e32 v226, 0x8000, v224
	global_load_lds_dwordx4 v226, s[18:19]
	s_add_u32 m0, m0, 0x400
	v_add_u32_e32 v226, 0xc000, v224
	global_load_lds_dwordx4 v226, s[18:19]
	s_add_u32 m0, m0, 0x400
	v_add_u32_e32 v226, 0x10000, v224
	global_load_lds_dwordx4 v226, s[18:19]
	s_add_u32 m0, m0, 0x400
	v_add_u32_e32 v226, 0x14000, v224
	global_load_lds_dwordx4 v226, s[18:19]
	s_add_u32 m0, m0, 0x400
	v_add_u32_e32 v226, 0x18000, v224
	global_load_lds_dwordx4 v226, s[18:19]
	s_add_u32 m0, m0, 0x400
	v_add_u32_e32 v226, 0x1c000, v224
	global_load_lds_dwordx4 v226, s[18:19]
	v_readfirstlane_b32 s32, v145
	s_lshl_b32 s32, s32, 2
	s_add_u32 m0, s32, 0x8000
	v_mov_b32_e32 v226, v225
	global_load_lds_dwordx4 v226, s[18:19]
	s_add_u32 m0, m0, 0x400
	v_add_u32_e32 v226, 0x4000, v225
	global_load_lds_dwordx4 v226, s[18:19]
	s_add_u32 m0, m0, 0x400
	v_add_u32_e32 v226, 0x8000, v225
	global_load_lds_dwordx4 v226, s[18:19]
	s_add_u32 m0, m0, 0x400
	v_add_u32_e32 v226, 0xc000, v225
	global_load_lds_dwordx4 v226, s[18:19]

.LBB0_542:
	s_mov_b32 s4, s2
	s_and_b32 s40, s4, 7
	s_cmp_lg_u32 s70, 0
	s_barrier
	s_cbranch_scc0 .LBB0_564
	v_mov_b32_e32 v1, v170
	s_nop 0
	v_cmp_eq_u32_e32 vcc, 0, v1
	s_and_saveexec_b64 s[30:31], vcc
	s_cbranch_execz .LBB0_545
	s_load_dword s4, s[60:61], 0x10
	s_waitcnt lgkmcnt(0)
	s_lshr_b32 s4, s4, 16
	s_cmp_lg_u32 s4, 0
	s_cselect_b64 s[4:5], -1, 0
	s_cmp_lg_u64 s[4:5], 0
	s_addc_u32 s4, s34, 0
	s_ashr_i32 s41, s4, 3
	s_lshl_b32 s4, s40, 2
	s_add_u32 s4, s63, s4
	s_addc_u32 s5, s64, 0
	v_mov_b64_e32 v[2:3], s[4:5]
	v_mov_b32_e32 v1, v253
	s_mov_b64 s[4:5], src_shared_base
	v_mov_b32_e32 v147, s5
	s_waitcnt vmcnt(0) lgkmcnt(0)
	v_add_u32_e32 v1, s41, v1
	flat_store_dword v[146:147], v1 sc0 sc1
	s_waitcnt vmcnt(0)

.LBB0_555:
	s_and_b64 vcc, exec, s[4:5]
	s_cbranch_vccz .LBB0_537
	v_mov_b32_e32 v1, v170
	s_ashr_i32 s31, s30, 31
	v_add_u32_e32 v2, s71, v1
	v_ashrrev_i32_e32 v3, 31, v2
	v_lshlrev_b64 v[2:3], 6, v[2:3]
	v_lshl_add_u64 v[2:3], s[14:15], 0, v[2:3]
	v_mov_b32_e32 v1, v170
	flat_load_dwordx4 v[14:17], v[2:3]
	flat_load_dwordx4 v[10:13], v[2:3] offset:16
	flat_load_dwordx4 v[6:9], v[2:3] offset:32
	s_nop 0
	flat_load_dwordx4 v[2:5], v[2:3] offset:48
	s_lshl_b64 s[6:7], s[30:31], 18
	v_lshlrev_b32_e32 v153, 4, v1
	v_bfe_u32 v51, v1, 2, 4
	v_ashrrev_i32_e32 v30, 2, v1
	v_add_u32_e32 v53, 0x1000, v153
	v_add_u32_e32 v54, 0x2000, v153
	v_add_u32_e32 v56, 0x3000, v153
	v_or_b32_e32 v28, s71, v51
	v_and_b32_e32 v22, -16, v30
	v_ashrrev_i32_e32 v35, 6, v53
	v_ashrrev_i32_e32 v26, 6, v54
	v_ashrrev_i32_e32 v29, 6, v56
	s_add_u32 s4, s57, s6
	v_and_b32_e32 v50, 32, v1
	v_add_u32_e32 v22, v28, v22
	v_and_b32_e32 v24, -16, v35
	v_and_b32_e32 v55, -16, v26
	v_and_b32_e32 v57, -16, v29
	s_addc_u32 s5, s62, s7
	v_bitop3_b32 v18, v153, v50, 48 bitop3:0x6c
	v_mov_b32_e32 v19, v0
	v_ashrrev_i32_e32 v23, 31, v22
	v_add_u32_e32 v24, v24, v28
	v_add_u32_e32 v26, v55, v28
	v_add_u32_e32 v28, v57, v28
	v_lshl_add_u64 v[20:21], s[8:9], 0, v[18:19]
	v_lshlrev_b64 v[22:23], 11, v[22:23]
	v_ashrrev_i32_e32 v25, 31, v24
	v_ashrrev_i32_e32 v27, 31, v26
	v_ashrrev_i32_e32 v29, 31, v28
	v_lshl_add_u64 v[18:19], s[4:5], 0, v[18:19]
	v_readfirstlane_b32 s4, v153
	v_lshrrev_b32_e32 v34, 2, v1
	v_lshl_add_u64 v[22:23], v[20:21], 0, v[22:23]
	v_lshlrev_b64 v[24:25], 11, v[24:25]
	v_lshlrev_b64 v[26:27], 11, v[26:27]
	v_lshlrev_b64 v[28:29], 11, v[28:29]
	s_waitcnt vmcnt(0)
	s_mov_b32 m0, s4
	v_readfirstlane_b32 s4, v53
	v_lshl_add_u64 v[24:25], v[20:21], 0, v[24:25]
	v_lshl_add_u64 v[26:27], v[20:21], 0, v[26:27]
	v_lshl_add_u64 v[20:21], v[20:21], 0, v[28:29]
	v_bfi_b32 v28, 15, v34, v30
	s_mov_b32 m0, s4
	v_readfirstlane_b32 s4, v54
	v_ashrrev_i32_e32 v29, 31, v28
	v_bfi_b32 v34, -16, v35, v34
	v_add_u32_e32 v58, 0x4000, v153
	s_mov_b32 m0, s4
	v_readfirstlane_b32 s4, v56
	v_lshlrev_b64 v[30:31], 11, v[28:29]
	v_ashrrev_i32_e32 v35, 31, v34
	v_add_u32_e32 v59, 0x5000, v153
	s_mov_b32 m0, s4
	v_readfirstlane_b32 s4, v58
	v_lshl_add_u64 v[32:33], v[18:19], 0, v[30:31]
	v_lshlrev_b64 v[36:37], 11, v[34:35]
	v_add_u32_e32 v60, 0x6000, v153
	s_mov_b32 m0, s4
	v_readfirstlane_b32 s4, v59
	v_and_b32_e32 v147, 15, v1
	v_lshl_add_u64 v[18:19], v[18:19], 0, v[36:37]
	v_bfe_u32 v149, v1, 4, 2
	v_lshlrev_b32_e32 v35, 6, v1
	v_lshlrev_b32_e32 v38, 2, v1
	v_add_u32_e32 v61, 0x7000, v153
	s_mov_b32 m0, s4
	v_readfirstlane_b32 s4, v60
	v_lshlrev_b32_e32 v29, 4, v149
	v_and_b32_e32 v40, 0x3c0, v35
	v_lshlrev_b32_e32 v41, 6, v147
	v_and_b32_e32 v42, 32, v38
	v_lshl_add_u64 v[38:39], v[22:23], 0, 64
	v_add_u32_e32 v62, 0x8000, v153
	s_mov_b32 m0, s4
	v_readfirstlane_b32 s4, v61
	v_add_u32_e32 v63, 0x9000, v153
	v_bitop3_b32 v157, v29, v42, v40 bitop3:0x36
	v_bitop3_b32 v151, v29, v42, v41 bitop3:0x36
	v_lshl_add_u64 v[40:41], v[24:25], 0, 64
	s_mov_b32 m0, s4
	v_readfirstlane_b32 s4, v62
	v_add_u32_e32 v64, 0xa000, v153
	v_lshl_add_u64 v[42:43], v[26:27], 0, 64
	s_mov_b32 m0, s4
	v_readfirstlane_b32 s4, v63
	v_add_u32_e32 v65, 0xb000, v153
	v_lshl_add_u64 v[44:45], v[20:21], 0, 64
	s_mov_b32 m0, s4
	v_readfirstlane_b32 s4, v64
	v_lshl_add_u64 v[46:47], v[32:33], 0, 64
	s_mov_b32 m0, s4
	v_readfirstlane_b32 s4, v65
	v_lshl_add_u64 v[48:49], v[18:19], 0, 64
	s_mov_b32 m0, s4
	v_and_b32_e32 v52, 48, v153
	v_lshl_add_u64 v[18:19], s[6:7], 0, v[36:37]
	v_bitop3_b32 v18, v18, v52, v50 bitop3:0xf6
	v_lshl_add_u64 v[158:159], s[26:27], 0, v[18:19]
	v_lshl_add_u64 v[18:19], s[6:7], 0, v[30:31]
	v_bitop3_b32 v18, v18, v52, v50 bitop3:0xf6
	v_lshl_add_u64 v[160:161], s[26:27], 0, v[18:19]
	v_add3_u32 v18, s71, v57, v51
	v_ashrrev_i32_e32 v19, 31, v18
	v_lshlrev_b64 v[18:19], 11, v[18:19]
	v_bitop3_b32 v18, v18, v52, v50 bitop3:0xf6
	v_lshl_add_u64 v[162:163], s[28:29], 0, v[18:19]
	v_add3_u32 v18, s71, v55, v51
	v_ashrrev_i32_e32 v19, 31, v18
	v_lshlrev_b64 v[18:19], 11, v[18:19]
	v_bitop3_b32 v18, v18, v52, v50 bitop3:0xf6
	v_lshl_add_u64 v[164:165], s[28:29], 0, v[18:19]
	v_add_u32_e32 v18, s71, v34
	v_ashrrev_i32_e32 v19, 31, v18
	v_lshlrev_b64 v[18:19], 11, v[18:19]
	v_bitop3_b32 v18, v18, v52, v50 bitop3:0xf6
	v_lshl_add_u64 v[166:167], s[28:29], 0, v[18:19]
	v_add_u32_e32 v18, s71, v28
	v_ashrrev_i32_e32 v19, 31, v18
	v_lshlrev_b64 v[18:19], 11, v[18:19]
	v_bitop3_b32 v18, v18, v52, v50 bitop3:0xf6
	v_lshl_add_u64 v[168:169], s[28:29], 0, v[18:19]
	v_mov_b32_e32 v18, 0
	v_and_b32_e32 v155, 0xfffff000, v35
	s_mov_b32 s4, 0
	s_mov_b64 s[6:7], 0
	v_mov_b32_e32 v19, v18
	v_mov_b32_e32 v20, v18
	v_mov_b32_e32 v21, v18
	v_mov_b32_e32 v22, v18
	v_mov_b32_e32 v23, v18
	v_mov_b32_e32 v24, v18
	v_mov_b32_e32 v25, v18
	v_mov_b32_e32 v26, v18
	v_mov_b32_e32 v27, v18
	v_mov_b32_e32 v28, v18
	v_mov_b32_e32 v29, v18
	v_mov_b32_e32 v34, v18
	v_mov_b32_e32 v35, v18
	v_mov_b32_e32 v36, v18
	v_mov_b32_e32 v37, v18
	v_mov_b32_e32 v42, v18
	v_mov_b32_e32 v43, v18
	v_mov_b32_e32 v44, v18
	v_mov_b32_e32 v45, v18
	v_mov_b32_e32 v54, v18
	v_mov_b32_e32 v55, v18
	v_mov_b32_e32 v56, v18
	v_mov_b32_e32 v57, v18
	v_mov_b32_e32 v62, v18
	v_mov_b32_e32 v63, v18
	v_mov_b32_e32 v64, v18
	v_mov_b32_e32 v65, v18
	v_mov_b32_e32 v78, v18
	v_mov_b32_e32 v79, v18
	v_mov_b32_e32 v80, v18
	v_mov_b32_e32 v81, v18
	v_mov_b32_e32 v30, v18
	v_mov_b32_e32 v31, v18
	v_mov_b32_e32 v32, v18
	v_mov_b32_e32 v33, v18
	v_mov_b32_e32 v38, v18
	v_mov_b32_e32 v39, v18
	v_mov_b32_e32 v40, v18
	v_mov_b32_e32 v41, v18
	v_mov_b32_e32 v46, v18
	v_mov_b32_e32 v47, v18
	v_mov_b32_e32 v48, v18
	v_mov_b32_e32 v49, v18
	v_mov_b32_e32 v58, v18
	v_mov_b32_e32 v59, v18
	v_mov_b32_e32 v60, v18
	v_mov_b32_e32 v61, v18
	v_mov_b32_e32 v70, v18
	v_mov_b32_e32 v71, v18
	v_mov_b32_e32 v72, v18
	v_mov_b32_e32 v73, v18
	v_mov_b32_e32 v86, v18
	v_mov_b32_e32 v87, v18
	v_mov_b32_e32 v88, v18
	v_mov_b32_e32 v89, v18
	v_mov_b32_e32 v94, v18
	v_mov_b32_e32 v95, v18
	v_mov_b32_e32 v96, v18
	v_mov_b32_e32 v97, v18
	v_mov_b32_e32 v110, v18
	v_mov_b32_e32 v111, v18
	v_mov_b32_e32 v112, v18
	v_mov_b32_e32 v113, v18
	v_mov_b32_e32 v50, v18
	v_mov_b32_e32 v51, v18
	v_mov_b32_e32 v52, v18
	v_mov_b32_e32 v53, v18
	v_mov_b32_e32 v66, v18
	v_mov_b32_e32 v67, v18
	v_mov_b32_e32 v68, v18
	v_mov_b32_e32 v69, v18
	v_mov_b32_e32 v74, v18
	v_mov_b32_e32 v75, v18
	v_mov_b32_e32 v76, v18
	v_mov_b32_e32 v77, v18
	v_mov_b32_e32 v90, v18
	v_mov_b32_e32 v91, v18
	v_mov_b32_e32 v92, v18
	v_mov_b32_e32 v93, v18
	v_mov_b32_e32 v102, v18
	v_mov_b32_e32 v103, v18
	v_mov_b32_e32 v104, v18
	v_mov_b32_e32 v105, v18
	v_mov_b32_e32 v114, v18
	v_mov_b32_e32 v115, v18
	v_mov_b32_e32 v116, v18
	v_mov_b32_e32 v117, v18
	v_mov_b32_e32 v122, v18
	v_mov_b32_e32 v123, v18
	v_mov_b32_e32 v124, v18
	v_mov_b32_e32 v125, v18
	v_mov_b32_e32 v130, v18
	v_mov_b32_e32 v131, v18
	v_mov_b32_e32 v132, v18
	v_mov_b32_e32 v133, v18
	v_mov_b32_e32 v82, v18
	v_mov_b32_e32 v83, v18
	v_mov_b32_e32 v84, v18
	v_mov_b32_e32 v85, v18
	v_mov_b32_e32 v98, v18
	v_mov_b32_e32 v99, v18
	v_mov_b32_e32 v100, v18
	v_mov_b32_e32 v101, v18
	v_mov_b32_e32 v106, v18
	v_mov_b32_e32 v107, v18
	v_mov_b32_e32 v108, v18
	v_mov_b32_e32 v109, v18
	v_mov_b32_e32 v118, v18
	v_mov_b32_e32 v119, v18
	v_mov_b32_e32 v120, v18
	v_mov_b32_e32 v121, v18
	v_mov_b32_e32 v126, v18
	v_mov_b32_e32 v127, v18
	v_mov_b32_e32 v128, v18
	v_mov_b32_e32 v129, v18
	v_mov_b32_e32 v134, v18
	v_mov_b32_e32 v135, v18
	v_mov_b32_e32 v136, v18
	v_mov_b32_e32 v137, v18
	v_mov_b32_e32 v138, v18
	v_mov_b32_e32 v139, v18
	v_mov_b32_e32 v140, v18
	v_mov_b32_e32 v141, v18
	v_mov_b32_e32 v142, v18
	v_mov_b32_e32 v143, v18
	v_mov_b32_e32 v144, v18
	v_mov_b32_e32 v145, v18
	s_and_b32 s32, s2, 7
	s_lshl_b32 s32, s32, 2
	s_add_u32 s4, s63, s32
	s_addc_u32 s5, s64, 0
	v_mov_b32_e32 v224, s4
	v_mov_b32_e32 v225, s5
	v_cmp_eq_u32_e32 vcc, 0, v170
	s_and_saveexec_b64 s[4:5], vcc
	global_atomic_add v253, v[224:225], v171, off sc0
	s_mov_b64 exec, s[4:5]
	v_and_b32_e32 v224, 63, v170
	v_lshrrev_b32_e32 v225, 3, v224
	v_and_b32_e32 v226, 7, v224
	v_xor_b32_e32 v226, v226, v225
	v_lshrrev_b32_e32 v227, 6, v170
	v_lshl_add_u32 v228, v227, 6, v225
	v_add_u32_e32 v228, s71, v228
	v_mul_u32_u24_e32 v240, 0x800, v228
	v_lshl_add_u32 v240, v226, 4, v240
	v_lshl_add_u32 v228, v227, 5, v225
	v_mul_u32_u24_e32 v241, 0x800, v228
	v_lshl_add_u32 v241, v226, 4, v241
	v_and_b32_e32 v225, 15, v224
	v_lshrrev_b32_e32 v226, 4, v224
	v_and_b32_e32 v228, 7, v225
	v_xor_b32_e32 v226, v226, v228
	v_lshlrev_b32_e32 v226, 4, v226
	v_lshl_add_u32 v245, v225, 7, v226
	v_lshl_add_u32 v243, v227, 13, v245
	v_xor_b32_e32 v244, 64, v243
	v_add_u32_e32 v245, 0x8000, v245
	v_xor_b32_e32 v246, 64, v245
	s_mov_b32 s4, s8
	s_mov_b32 s5, s9
	s_lshl_b32 s32, s30, 18
	s_add_u32 s6, s57, s32
	s_addc_u32 s7, s62, 0
	s_mov_b32 s31, 0
	v_readfirstlane_b32 s32, v153
	s_lshl_b32 m0, s32, 3
	v_mov_b32_e32 v242, v240
	global_load_lds_dwordx4 v242, s[4:5]
	s_add_u32 m0, m0, 0x400
	v_add_u32_e32 v242, 0x4000, v240
	global_load_lds_dwordx4 v242, s[4:5]
	s_add_u32 m0, m0, 0x400
	v_add_u32_e32 v242, 0x8000, v240
	global_load_lds_dwordx4 v242, s[4:5]
	s_add_u32 m0, m0, 0x400
	v_add_u32_e32 v242, 0xc000, v240
	global_load_lds_dwordx4 v242, s[4:5]
	s_add_u32 m0, m0, 0x400
	v_add_u32_e32 v242, 0x10000, v240
	global_load_lds_dwordx4 v242, s[4:5]
	s_add_u32 m0, m0, 0x400
	v_add_u32_e32 v242, 0x14000, v240
	global_load_lds_dwordx4 v242, s[4:5]
	s_add_u32 m0, m0, 0x400
	v_add_u32_e32 v242, 0x18000, v240
	global_load_lds_dwordx4 v242, s[4:5]
	s_add_u32 m0, m0, 0x400
	v_add_u32_e32 v242, 0x1c000, v240
	global_load_lds_dwordx4 v242, s[4:5]
	v_readfirstlane_b32 s32, v153
	s_lshl_b32 s32, s32, 2
	s_add_u32 m0, s32, 0x8000
	v_mov_b32_e32 v242, v241
	global_load_lds_dwordx4 v242, s[6:7]
	s_add_u32 m0, m0, 0x400
	v_add_u32_e32 v242, 0x4000, v241
	global_load_lds_dwordx4 v242, s[6:7]
	s_add_u32 m0, m0, 0x400
	v_add_u32_e32 v242, 0x8000, v241
	global_load_lds_dwordx4 v242, s[6:7]
	s_add_u32 m0, m0, 0x400
	v_add_u32_e32 v242, 0xc000, v241
	global_load_lds_dwordx4 v242, s[6:7]
